# adds: attention V-transpose LDS tile row stride 144B->152B (bank-conflict fix for b16 transpose writes and PV fragment reads)
# speedup vs baseline: 1.0712x; 1.0168x over previous
.LBB0_337:
	s_andn2_b64 vcc, exec, s[44:45]
	s_cbranch_vccnz .LBB0_447
	v_readlane_b32 s38, v254, 28
	v_readlane_b32 s46, v253, 2
	v_readlane_b32 s39, v254, 29
	v_readlane_b32 s47, v253, 3
	v_mov_b32_e32 v0, v133
	s_andn2_b64 vcc, exec, s[38:39]
	s_cbranch_vccnz .LBB0_384
	v_ashrrev_i32_e32 v4, 3, v0
	v_ashrrev_i32_e32 v5, 31, v4
	s_load_dwordx2 s[44:45], s[46:47], 0xf8
	s_nop 0
	s_load_dwordx2 s[46:47], s[46:47], 0xc0
	v_lshlrev_b64 v[6:7], 8, v[4:5]
	v_lshlrev_b32_e32 v5, 3, v0
	v_and_b32_e32 v8, 56, v5
	v_add_u32_e32 v5, 0x100, v0
	v_ashrrev_i32_e32 v10, 3, v5
	v_bfe_u32 v3, v0, 5, 1
	v_ashrrev_i32_e32 v11, 31, v10
	v_and_b32_e32 v14, 64, v188
	s_waitcnt lgkmcnt(0)
	s_add_u32 s48, s44, 0x22600000
	v_cmp_eq_u32_e32 vcc, 0, v3
	v_lshlrev_b64 v[12:13], 8, v[10:11]
	v_xor_b32_e32 v11, 32, v188
	v_add_u32_e32 v14, 64, v14
	v_ashrrev_i32_e32 v2, 1, v0
	s_addc_u32 s49, s45, 0
	s_movk_i32 s3, 0xffe0
	v_cndmask_b32_e64 v107, 0, 1.0, vcc
	v_and_b32_e32 v5, 7, v0
	v_cmp_lt_i32_e32 vcc, v11, v14
	v_readlane_b32 s38, v254, 60
	v_and_b32_e32 v1, 31, v0
	s_add_u32 s50, s44, 0x31600000
	v_bfi_b32 v106, s3, v2, v0
	v_lshlrev_b32_e32 v2, 3, v3
	v_lshlrev_b32_e32 v9, 4, v5
	s_waitcnt vmcnt(0)
	v_lshlrev_b32_e32 v108, 4, v3
	v_cndmask_b32_e32 v11, v188, v11, vcc
	s_movk_i32 s3, 0x4b0
	v_readlane_b32 s39, v254, 61
	s_addc_u32 s51, s45, 0
	v_lshlrev_b32_e32 v0, 2, v3
	v_sub_u32_e32 v3, v108, v2
	v_lshlrev_b32_e32 v109, 2, v11
	v_mul_lo_u32 v11, v4, s85
	v_lshlrev_b32_e32 v4, 1, v4
	v_mad_u32_u24 v5, v5, s3, v9
	v_mul_lo_u32 v14, v10, s85
	v_lshlrev_b32_e32 v10, 1, v10
	v_mul_u32_u24_e32 v110, 0x90, v1
	s_lshl_b32 s3, s38, 4
	s_lshl_b32 s52, s38, 17
	v_readlane_b32 s38, v253, 0
	s_mov_b32 s53, s81
	v_or_b32_e32 v111, 0x80, v0
	v_lshlrev_b32_e32 v96, 1, v2
	v_lshlrev_b32_e32 v128, 1, v8
	v_add_u32_e32 v112, v9, v11
	v_add_u32_e32 v113, v5, v4
	v_add_u32_e32 v114, v9, v14
	v_add_u32_e32 v115, v5, v10
	v_add_u32_e32 v116, v3, v110
	v_lshl_add_u32 v116, v1, 3, v116
	v_lshlrev_b32_e32 v98, 1, v0
	v_lshlrev_b64 v[100:101], 1, v[6:7]
	v_lshlrev_b64 v[102:103], 1, v[12:13]
	s_mov_b32 s31, s38
	v_readlane_b32 s39, v253, 1
	s_branch .LBB0_341

.LBB0_368:
	s_add_i32 s94, s96, 1
	s_cmp_ge_u32 s94, s78
	s_barrier
	s_waitcnt vmcnt(3)
	ds_write_b128 v112, v[64:67]
	s_waitcnt vmcnt(2)
	ds_write_b16 v113, v68 offset:9216
	ds_write_b16_d16_hi v113, v68 offset:9368
	ds_write_b16 v113, v69 offset:9520
	ds_write_b16_d16_hi v113, v69 offset:9672
	ds_write_b16 v113, v70 offset:9824
	ds_write_b16_d16_hi v113, v70 offset:9976
	ds_write_b16 v113, v71 offset:10128
	ds_write_b16_d16_hi v113, v71 offset:10280
	s_waitcnt vmcnt(1)
	ds_write_b128 v114, v[80:83]
	s_waitcnt vmcnt(0)
	ds_write_b16 v115, v88 offset:9216
	ds_write_b16_d16_hi v115, v88 offset:9368
	ds_write_b16 v115, v89 offset:9520
	ds_write_b16_d16_hi v115, v89 offset:9672
	ds_write_b16 v115, v90 offset:9824
	ds_write_b16_d16_hi v115, v90 offset:9976
	ds_write_b16 v115, v91 offset:10128
	ds_write_b16_d16_hi v115, v91 offset:10280
	s_waitcnt lgkmcnt(0)
	s_barrier
	s_cbranch_scc1 .LBB0_379
	s_and_b64 vcc, exec, s[56:57]
	s_cbranch_vccz .LBB0_371
	s_lshl_b64 s[66:67], s[80:81], 8
	s_add_u32 s66, s66, s58
	s_addc_u32 s67, s67, s59
	s_mov_b64 s[72:73], -1
	s_cbranch_execz .LBB0_372
	s_branch .LBB0_376

.LBB0_381:
	v_sub_f32_e32 v40, v48, v51
	v_exp_f32_e32 v44, v40
	v_sub_f32_e32 v40, v49, v51
	v_sub_f32_e32 v41, v50, v51
	v_exp_f32_e32 v45, v40
	v_exp_f32_e32 v46, v41
	v_sub_f32_e32 v41, v118, v51
	v_exp_f32_e32 v47, v41
	v_sub_f32_e32 v41, v52, v51
	v_add_f32_e32 v40, v44, v99
	v_exp_f32_e32 v48, v41
	v_sub_f32_e32 v41, v53, v51
	v_add_f32_e32 v40, v45, v40
	v_exp_f32_e32 v49, v41
	v_sub_f32_e32 v41, v54, v51
	v_add_f32_e32 v40, v46, v40
	v_exp_f32_e32 v50, v41
	v_sub_f32_e32 v41, v119, v51
	v_add_f32_e32 v40, v47, v40
	v_exp_f32_e32 v52, v41
	v_sub_f32_e32 v41, v121, v51
	v_add_f32_e32 v40, v48, v40
	v_exp_f32_e32 v53, v41
	v_add_f32_e32 v40, v49, v40
	v_add_f32_e32 v40, v50, v40
	v_add_f32_e32 v40, v52, v40
	v_add_f32_e32 v99, v53, v40
	v_sub_f32_e32 v40, v120, v51
	v_exp_f32_e32 v117, v40
	v_sub_f32_e32 v40, v122, v51
	v_exp_f32_e32 v118, v40
	v_sub_f32_e32 v40, v123, v51
	v_exp_f32_e32 v119, v40
	v_sub_f32_e32 v40, v60, v51
	v_exp_f32_e32 v120, v40
	v_sub_f32_e32 v40, v61, v51
	v_exp_f32_e32 v121, v40
	v_sub_f32_e32 v40, v62, v51
	v_exp_f32_e32 v122, v40
	v_sub_f32_e32 v40, v63, v51
	v_exp_f32_e32 v123, v40
	v_sub_f32_e32 v40, v124, v51
	v_exp_f32_e32 v124, v40
	v_sub_f32_e32 v40, v125, v51
	v_exp_f32_e32 v125, v40
	v_sub_f32_e32 v40, v126, v51
	v_add_u32_e32 v127, 0x2000, v116
	v_exp_f32_e32 v126, v40
	ds_read2_b64 v[40:43], v127 offset0:128 offset1:130
	v_cvt_pk_bf16_f32 v44, v44, v45
	v_cvt_pk_bf16_f32 v45, v46, v47
	v_cvt_pk_bf16_f32 v46, v48, v49
	v_cvt_pk_bf16_f32 v47, v50, v52
	v_add_u32_e32 v50, 0x3000, v116
	ds_read2_b64 v[60:63], v50 offset0:224 offset1:226
	s_waitcnt lgkmcnt(1)
	v_mfma_f32_32x32x16_bf16 v[16:31], v[40:43], v[44:47], v[16:31]
	v_sub_f32_e32 v40, v56, v51
	v_exp_f32_e32 v56, v40
	v_sub_f32_e32 v40, v57, v51
	v_exp_f32_e32 v57, v40
	v_sub_f32_e32 v40, v58, v51
	v_exp_f32_e32 v58, v40
	ds_read2_b64 v[40:43], v127 offset0:132 offset1:134
	v_sub_f32_e32 v54, v59, v51
	s_waitcnt lgkmcnt(1)
	v_mfma_f32_32x32x16_bf16 v[0:15], v[60:63], v[44:47], v[0:15]
	v_sub_f32_e32 v44, v55, v51
	v_exp_f32_e32 v59, v54
	v_exp_f32_e32 v60, v44
	v_cvt_pk_bf16_f32 v44, v53, v117
	ds_read2_b64 v[52:55], v50 offset0:228 offset1:230
	v_sub_f32_e32 v37, v37, v51
	v_cvt_pk_bf16_f32 v45, v118, v119
	v_cvt_pk_bf16_f32 v46, v120, v121
	v_cvt_pk_bf16_f32 v47, v122, v123
	v_exp_f32_e32 v61, v37
	v_sub_f32_e32 v37, v38, v51
	s_waitcnt lgkmcnt(1)
	v_mfma_f32_32x32x16_bf16 v[16:31], v[40:43], v[44:47], v[16:31]
	v_exp_f32_e32 v62, v37
	v_sub_f32_e32 v37, v39, v51
	ds_read2_b64 v[38:41], v127 offset0:136 offset1:138
	v_sub_f32_e32 v34, v34, v51
	v_sub_f32_e32 v36, v36, v51
	v_exp_f32_e32 v63, v37
	v_cvt_pk_bf16_f32 v42, v124, v125
	s_waitcnt lgkmcnt(1)
	v_mfma_f32_32x32x16_bf16 v[0:15], v[52:55], v[44:47], v[0:15]
	v_exp_f32_e32 v53, v34
	v_sub_f32_e32 v34, v35, v51
	v_exp_f32_e32 v52, v36
	v_cvt_pk_bf16_f32 v43, v126, v59
	v_cvt_pk_bf16_f32 v44, v56, v57
	v_cvt_pk_bf16_f32 v45, v58, v60
	v_exp_f32_e32 v54, v34
	ds_read2_b64 v[34:37], v127 offset0:140 offset1:142
	s_waitcnt lgkmcnt(1)
	v_mfma_f32_32x32x16_bf16 v[16:31], v[38:41], v[42:45], v[16:31]
	v_sub_f32_e32 v33, v33, v51
	v_sub_f32_e32 v32, v32, v51
	v_exp_f32_e32 v33, v33
	v_exp_f32_e32 v32, v32
	ds_read2_b64 v[46:49], v50 offset0:232 offset1:234
	v_cvt_pk_bf16_f32 v38, v61, v62
	v_cvt_pk_bf16_f32 v39, v63, v52
	v_cvt_pk_bf16_f32 v40, v33, v53
	v_cvt_pk_bf16_f32 v41, v54, v32
	s_waitcnt lgkmcnt(0)
	v_mfma_f32_32x32x16_bf16 v[0:15], v[46:49], v[42:45], v[0:15]
	ds_read2_b64 v[42:45], v50 offset0:236 offset1:238
	v_mfma_f32_32x32x16_bf16 v[16:31], v[34:37], v[38:41], v[16:31]
	v_add_f32_e32 v34, v117, v99
	v_add_f32_e32 v34, v118, v34
	v_add_f32_e32 v34, v119, v34
	v_add_f32_e32 v34, v120, v34
	v_add_f32_e32 v34, v121, v34
	v_add_f32_e32 v34, v122, v34
	v_add_f32_e32 v34, v123, v34
	v_add_f32_e32 v34, v124, v34
	v_add_f32_e32 v34, v125, v34
	v_add_f32_e32 v34, v126, v34
	v_add_f32_e32 v34, v59, v34
	v_add_f32_e32 v34, v56, v34
	v_add_f32_e32 v34, v57, v34
	v_add_f32_e32 v34, v58, v34
	v_add_f32_e32 v34, v60, v34
	s_waitcnt lgkmcnt(0)
	v_mfma_f32_32x32x16_bf16 v[0:15], v[42:45], v[38:41], v[0:15]
	v_add_f32_e32 v34, v61, v34
	v_add_f32_e32 v34, v62, v34
	v_add_f32_e32 v34, v63, v34
	v_add_f32_e32 v34, v52, v34
	v_add_f32_e32 v33, v33, v34
	v_add_f32_e32 v33, v53, v33
	v_add_f32_e32 v33, v54, v33
	v_add_f32_e32 v99, v32, v33
	s_add_i32 s80, s80, 64
	s_addk_i32 s93, 0x4000
	s_cmp_eq_u32 s78, s94
	s_cbranch_scc0 .LBB0_348
	s_branch .LBB0_340
